# static unit order in incremental form for the Z and RES GEMM instances (no integer divisions per tile)
# speedup vs baseline: 1.0121x; 1.0065x over previous
;     __device__ bool next(int i, Unit& u) const {
;         const long L = (long)i * G + c; if (L >= nwg) return false;
;         int wgid = (int)L; { const int q = nwg / NXCD, r = nwg % NXCD, xcd = wgid % NXCD, off = wgid / NXCD; wgid = (xcd < r ? xcd * (q + 1) : r * (q + 1) + (xcd - r) * q) + off; }
;         const int nig = wgm * nN, gid = wgid / nig, fm = gid * wgm, gsz = (nM - fm) < wgm ? (nM - fm) : wgm;
;         u.pm = fm + ((wgid % nig) % gsz); u.pn = (wgid % nig) / gsz; return true;
;     }
; template <class Epi>
; __device__ __forceinline__ void gemm_phase(LAS unsigned char* lds, const Gemm g, const StaticOrder& S, const Epi& E, const int tid) {
;     ...
;         const bool has_next = S.next(ui + 1, nxt);
.LBB0_286:
	s_add_i32 s53, s53, 1
	s_waitcnt lgkmcnt(0)
	s_cmp_lt_u32 s53, 2
	s_cselect_b64 s[6:7], -1, 0
	s_mov_b32 s54, s56
	s_add_i32 s55, s57, 8

;     __device__ bool next(int i, Unit& u) const {
;         const long L = (long)i * G + c; if (L >= nwg) return false;
;         int wgid = (int)L; { const int q = nwg / NXCD, r = nwg % NXCD, xcd = wgid % NXCD, off = wgid / NXCD; wgid = (xcd < r ? xcd * (q + 1) : r * (q + 1) + (xcd - r) * q) + off; }
;         const int nig = wgm * nN, gid = wgid / nig, fm = gid * wgm, gsz = (nM - fm) < wgm ? (nM - fm) : wgm;
;         u.pm = fm + ((wgid % nig) % gsz); u.pn = (wgid % nig) / gsz; return true;
;     }
; template <class Epi>
; __device__ __forceinline__ void gemm_phase(LAS unsigned char* lds, const Gemm g, const StaticOrder& S, const Epi& E, const int tid) {
;     ...
;         const bool has_next = S.next(ui + 1, nxt);
.LBB0_419:
	s_add_i32 s42, s42, 1
	s_waitcnt lgkmcnt(0)
	s_lshr_b32 s0, s41, 4
	s_cmp_lt_u32 s42, s0
	s_cselect_b64 s[6:7], -1, 0
	s_cbranch_scc0 .LBB0_421
	s_add_i32 s78, s89, 4
	s_mov_b32 s72, s79
	s_lshr_b32 s0, s41, 3
	s_cmp_lt_i32 s78, s0
	s_cbranch_scc1 .LBB0_421
	s_sub_i32 s78, s78, s0
	s_add_i32 s72, s79, 8
